# P3 mask finalize: per-key-register lane-0 ds_write chain replaced by v_cmp + v_writelane per register and one 31-lane ds_write_b64 (both queries, both indexer copies)
# speedup vs baseline: 1.0598x; 1.0150x over previous
.LBB0_736:
	s_cmp_lg_u32 s1, 0
	s_cselect_b64 s[2:3], -1, 0
	s_and_b64 s[2:3], s[2:3], s[8:9]
	s_andn2_b64 vcc, exec, s[2:3]
	s_cbranch_vccz .LBB0_770
	s_max_u32 s2, s1, 1
	v_cmp_le_u32_e64 s[10:11], s2, v245
	v_cmp_le_u32_e64 s[50:51], s2, v244
	v_cmp_le_u32_e64 s[52:53], s2, v243
	v_writelane_b32 v248, s10, 0
	v_writelane_b32 v249, s11, 0
	v_cmp_le_u32_e64 s[10:11], s2, v242
	v_writelane_b32 v248, s50, 1
	v_writelane_b32 v249, s51, 1
	v_cmp_le_u32_e64 s[50:51], s2, v241
	v_writelane_b32 v248, s52, 2
	v_writelane_b32 v249, s53, 2
	v_cmp_le_u32_e64 s[52:53], s2, v240
	v_writelane_b32 v248, s10, 3
	v_writelane_b32 v249, s11, 3
	v_cmp_le_u32_e64 s[10:11], s2, v239
	v_writelane_b32 v248, s50, 4
	v_writelane_b32 v249, s51, 4
	v_cmp_le_u32_e64 s[50:51], s2, v238
	v_writelane_b32 v248, s52, 5
	v_writelane_b32 v249, s53, 5
	v_cmp_le_u32_e64 s[52:53], s2, v237
	v_writelane_b32 v248, s10, 6
	v_writelane_b32 v249, s11, 6
	v_cmp_le_u32_e64 s[10:11], s2, v236
	v_writelane_b32 v248, s50, 7
	v_writelane_b32 v249, s51, 7
	v_cmp_le_u32_e64 s[50:51], s2, v235
	v_writelane_b32 v248, s52, 8
	v_writelane_b32 v249, s53, 8
	v_cmp_le_u32_e64 s[52:53], s2, v234
	v_writelane_b32 v248, s10, 9
	v_writelane_b32 v249, s11, 9
	v_cmp_le_u32_e64 s[10:11], s2, v233
	v_writelane_b32 v248, s50, 10
	v_writelane_b32 v249, s51, 10
	v_cmp_le_u32_e64 s[50:51], s2, v232
	v_writelane_b32 v248, s52, 11
	v_writelane_b32 v249, s53, 11
	v_cmp_le_u32_e64 s[52:53], s2, v231
	v_writelane_b32 v248, s10, 12
	v_writelane_b32 v249, s11, 12
	v_cmp_le_u32_e64 s[10:11], s2, v230
	v_writelane_b32 v248, s50, 13
	v_writelane_b32 v249, s51, 13
	v_cmp_le_u32_e64 s[50:51], s2, v229
	v_writelane_b32 v248, s52, 14
	v_writelane_b32 v249, s53, 14
	v_cmp_le_u32_e64 s[52:53], s2, v228
	v_writelane_b32 v248, s10, 15
	v_writelane_b32 v249, s11, 15
	v_cmp_le_u32_e64 s[10:11], s2, v227
	v_writelane_b32 v248, s50, 16
	v_writelane_b32 v249, s51, 16
	v_cmp_le_u32_e64 s[50:51], s2, v226
	v_writelane_b32 v248, s52, 17
	v_writelane_b32 v249, s53, 17
	v_cmp_le_u32_e64 s[52:53], s2, v225
	v_writelane_b32 v248, s10, 18
	v_writelane_b32 v249, s11, 18
	v_cmp_le_u32_e64 s[10:11], s2, v224
	v_writelane_b32 v248, s50, 19
	v_writelane_b32 v249, s51, 19
	v_cmp_le_u32_e64 s[50:51], s2, v223
	v_writelane_b32 v248, s52, 20
	v_writelane_b32 v249, s53, 20
	v_cmp_le_u32_e64 s[52:53], s2, v222
	v_writelane_b32 v248, s10, 21
	v_writelane_b32 v249, s11, 21
	v_cmp_le_u32_e64 s[10:11], s2, v221
	v_writelane_b32 v248, s50, 22
	v_writelane_b32 v249, s51, 22
	v_cmp_le_u32_e64 s[50:51], s2, v220
	v_writelane_b32 v248, s52, 23
	v_writelane_b32 v249, s53, 23
	v_cmp_le_u32_e64 s[52:53], s2, v219
	v_writelane_b32 v248, s10, 24
	v_writelane_b32 v249, s11, 24
	v_cmp_le_u32_e64 s[10:11], s2, v218
	v_writelane_b32 v248, s50, 25
	v_writelane_b32 v249, s51, 25
	v_cmp_le_u32_e64 s[50:51], s2, v217
	v_writelane_b32 v248, s52, 26
	v_writelane_b32 v249, s53, 26
	v_cmp_le_u32_e64 s[52:53], s2, v216
	v_writelane_b32 v248, s10, 27
	v_writelane_b32 v249, s11, 27
	v_cmp_le_u32_e64 s[10:11], s2, v77
	v_writelane_b32 v248, s50, 28
	v_writelane_b32 v249, s51, 28
	s_nop 1
	v_writelane_b32 v248, s52, 29
	v_writelane_b32 v249, s53, 29
	s_nop 1
	v_writelane_b32 v248, s10, 30
	v_writelane_b32 v249, s11, 30
	v_lshl_add_u32 v246, v130, 3, s6
	s_mov_b64 s[50:51], exec
	s_mov_b64 exec, 0x7fffffff
	ds_write_b64 v246, v[248:249]
	s_mov_b64 exec, s[50:51]
	v_cmp_le_u32_e64 s[10:11], s2, v76
	s_mov_b64 s[76:77], s[86:87]
	s_branch .LBB0_1086
	v_cmp_le_u32_e64 s[10:11], s2, v245
	s_and_saveexec_b64 s[8:9], s[86:87]
	s_cbranch_execz .LBB0_776
	v_mov_b32_e32 v246, s6
	v_mov_b64_e32 v[248:249], s[10:11]
	ds_write_b64 v246, v[248:249]
	s_or_b64 exec, exec, s[8:9]
	v_cmp_le_u32_e64 s[10:11], s2, v244
	s_and_saveexec_b64 s[8:9], s[86:87]
	s_cbranch_execnz .LBB0_777

.LBB0_1090:
	s_or_b64 exec, exec, s[10:11]
	s_cmp_lg_u32 s0, 0
	s_cselect_b64 s[2:3], -1, 0
	s_and_b64 s[2:3], s[2:3], s[72:73]
	s_andn2_b64 vcc, exec, s[2:3]
	s_cbranch_vccz .LBB0_1125
	s_max_u32 s2, s0, 1
	v_cmp_le_u32_e64 s[12:13], s2, v215
	v_cmp_le_u32_e64 s[50:51], s2, v108
	v_cmp_le_u32_e64 s[52:53], s2, v107
	v_writelane_b32 v218, s12, 0
	v_writelane_b32 v219, s13, 0
	v_cmp_le_u32_e64 s[12:13], s2, v106
	v_writelane_b32 v218, s50, 1
	v_writelane_b32 v219, s51, 1
	v_cmp_le_u32_e64 s[50:51], s2, v105
	v_writelane_b32 v218, s52, 2
	v_writelane_b32 v219, s53, 2
	v_cmp_le_u32_e64 s[52:53], s2, v104
	v_writelane_b32 v218, s12, 3
	v_writelane_b32 v219, s13, 3
	v_cmp_le_u32_e64 s[12:13], s2, v103
	v_writelane_b32 v218, s50, 4
	v_writelane_b32 v219, s51, 4
	v_cmp_le_u32_e64 s[50:51], s2, v102
	v_writelane_b32 v218, s52, 5
	v_writelane_b32 v219, s53, 5
	v_cmp_le_u32_e64 s[52:53], s2, v101
	v_writelane_b32 v218, s12, 6
	v_writelane_b32 v219, s13, 6
	v_cmp_le_u32_e64 s[12:13], s2, v100
	v_writelane_b32 v218, s50, 7
	v_writelane_b32 v219, s51, 7
	v_cmp_le_u32_e64 s[50:51], s2, v99
	v_writelane_b32 v218, s52, 8
	v_writelane_b32 v219, s53, 8
	v_cmp_le_u32_e64 s[52:53], s2, v98
	v_writelane_b32 v218, s12, 9
	v_writelane_b32 v219, s13, 9
	v_cmp_le_u32_e64 s[12:13], s2, v97
	v_writelane_b32 v218, s50, 10
	v_writelane_b32 v219, s51, 10
	v_cmp_le_u32_e64 s[50:51], s2, v96
	v_writelane_b32 v218, s52, 11
	v_writelane_b32 v219, s53, 11
	v_cmp_le_u32_e64 s[52:53], s2, v95
	v_writelane_b32 v218, s12, 12
	v_writelane_b32 v219, s13, 12
	v_cmp_le_u32_e64 s[12:13], s2, v94
	v_writelane_b32 v218, s50, 13
	v_writelane_b32 v219, s51, 13
	v_cmp_le_u32_e64 s[50:51], s2, v93
	v_writelane_b32 v218, s52, 14
	v_writelane_b32 v219, s53, 14
	v_cmp_le_u32_e64 s[52:53], s2, v92
	v_writelane_b32 v218, s12, 15
	v_writelane_b32 v219, s13, 15
	v_cmp_le_u32_e64 s[12:13], s2, v91
	v_writelane_b32 v218, s50, 16
	v_writelane_b32 v219, s51, 16
	v_cmp_le_u32_e64 s[50:51], s2, v90
	v_writelane_b32 v218, s52, 17
	v_writelane_b32 v219, s53, 17
	v_cmp_le_u32_e64 s[52:53], s2, v89
	v_writelane_b32 v218, s12, 18
	v_writelane_b32 v219, s13, 18
	v_cmp_le_u32_e64 s[12:13], s2, v88
	v_writelane_b32 v218, s50, 19
	v_writelane_b32 v219, s51, 19
	v_cmp_le_u32_e64 s[50:51], s2, v87
	v_writelane_b32 v218, s52, 20
	v_writelane_b32 v219, s53, 20
	v_cmp_le_u32_e64 s[52:53], s2, v86
	v_writelane_b32 v218, s12, 21
	v_writelane_b32 v219, s13, 21
	v_cmp_le_u32_e64 s[12:13], s2, v85
	v_writelane_b32 v218, s50, 22
	v_writelane_b32 v219, s51, 22
	v_cmp_le_u32_e64 s[50:51], s2, v84
	v_writelane_b32 v218, s52, 23
	v_writelane_b32 v219, s53, 23
	v_cmp_le_u32_e64 s[52:53], s2, v83
	v_writelane_b32 v218, s12, 24
	v_writelane_b32 v219, s13, 24
	v_cmp_le_u32_e64 s[12:13], s2, v82
	v_writelane_b32 v218, s50, 25
	v_writelane_b32 v219, s51, 25
	v_cmp_le_u32_e64 s[50:51], s2, v81
	v_writelane_b32 v218, s52, 26
	v_writelane_b32 v219, s53, 26
	v_cmp_le_u32_e64 s[52:53], s2, v80
	v_writelane_b32 v218, s12, 27
	v_writelane_b32 v219, s13, 27
	v_cmp_le_u32_e64 s[12:13], s2, v79
	v_writelane_b32 v218, s50, 28
	v_writelane_b32 v219, s51, 28
	s_nop 1
	v_writelane_b32 v218, s52, 29
	v_writelane_b32 v219, s53, 29
	s_nop 1
	v_writelane_b32 v218, s12, 30
	v_writelane_b32 v219, s13, 30
	v_lshl_add_u32 v216, v130, 3, s6
	s_mov_b64 s[50:51], exec
	s_mov_b64 exec, 0x7fffffff
	ds_write_b64 v216, v[218:219] offset:256
	s_mov_b64 exec, s[50:51]
	v_cmp_le_u32_e64 s[12:13], s2, v78
	s_mov_b64 s[76:77], s[86:87]
	s_branch .LBB0_1124
	v_cmp_le_u32_e64 s[12:13], s2, v215
	s_and_saveexec_b64 s[10:11], s[86:87]
	s_cbranch_execz .LBB0_1131
	v_mov_b32_e32 v216, s6
	v_mov_b64_e32 v[218:219], s[12:13]
	ds_write_b64 v216, v[218:219] offset:256
	s_or_b64 exec, exec, s[10:11]
	v_cmp_le_u32_e64 s[12:13], s2, v108
	s_and_saveexec_b64 s[10:11], s[86:87]
	s_cbranch_execnz .LBB0_1132

.LBB0_1743:
	s_cmp_lg_u32 s1, 0
	s_cselect_b64 s[2:3], -1, 0
	s_and_b64 s[2:3], s[2:3], s[4:5]
	s_andn2_b64 vcc, exec, s[2:3]
	s_cbranch_vccz .LBB0_1777
	s_max_u32 s2, s1, 1
	v_cmp_le_u32_e64 s[8:9], s2, v241
	v_cmp_le_u32_e64 s[50:51], s2, v240
	v_cmp_le_u32_e64 s[52:53], s2, v239
	v_writelane_b32 v244, s8, 0
	v_writelane_b32 v245, s9, 0
	v_cmp_le_u32_e64 s[8:9], s2, v238
	v_writelane_b32 v244, s50, 1
	v_writelane_b32 v245, s51, 1
	v_cmp_le_u32_e64 s[50:51], s2, v237
	v_writelane_b32 v244, s52, 2
	v_writelane_b32 v245, s53, 2
	v_cmp_le_u32_e64 s[52:53], s2, v236
	v_writelane_b32 v244, s8, 3
	v_writelane_b32 v245, s9, 3
	v_cmp_le_u32_e64 s[8:9], s2, v235
	v_writelane_b32 v244, s50, 4
	v_writelane_b32 v245, s51, 4
	v_cmp_le_u32_e64 s[50:51], s2, v234
	v_writelane_b32 v244, s52, 5
	v_writelane_b32 v245, s53, 5
	v_cmp_le_u32_e64 s[52:53], s2, v233
	v_writelane_b32 v244, s8, 6
	v_writelane_b32 v245, s9, 6
	v_cmp_le_u32_e64 s[8:9], s2, v232
	v_writelane_b32 v244, s50, 7
	v_writelane_b32 v245, s51, 7
	v_cmp_le_u32_e64 s[50:51], s2, v231
	v_writelane_b32 v244, s52, 8
	v_writelane_b32 v245, s53, 8
	v_cmp_le_u32_e64 s[52:53], s2, v230
	v_writelane_b32 v244, s8, 9
	v_writelane_b32 v245, s9, 9
	v_cmp_le_u32_e64 s[8:9], s2, v229
	v_writelane_b32 v244, s50, 10
	v_writelane_b32 v245, s51, 10
	v_cmp_le_u32_e64 s[50:51], s2, v228
	v_writelane_b32 v244, s52, 11
	v_writelane_b32 v245, s53, 11
	v_cmp_le_u32_e64 s[52:53], s2, v227
	v_writelane_b32 v244, s8, 12
	v_writelane_b32 v245, s9, 12
	v_cmp_le_u32_e64 s[8:9], s2, v226
	v_writelane_b32 v244, s50, 13
	v_writelane_b32 v245, s51, 13
	v_cmp_le_u32_e64 s[50:51], s2, v225
	v_writelane_b32 v244, s52, 14
	v_writelane_b32 v245, s53, 14
	v_cmp_le_u32_e64 s[52:53], s2, v224
	v_writelane_b32 v244, s8, 15
	v_writelane_b32 v245, s9, 15
	v_cmp_le_u32_e64 s[8:9], s2, v223
	v_writelane_b32 v244, s50, 16
	v_writelane_b32 v245, s51, 16
	v_cmp_le_u32_e64 s[50:51], s2, v222
	v_writelane_b32 v244, s52, 17
	v_writelane_b32 v245, s53, 17
	v_cmp_le_u32_e64 s[52:53], s2, v221
	v_writelane_b32 v244, s8, 18
	v_writelane_b32 v245, s9, 18
	v_cmp_le_u32_e64 s[8:9], s2, v220
	v_writelane_b32 v244, s50, 19
	v_writelane_b32 v245, s51, 19
	v_cmp_le_u32_e64 s[50:51], s2, v219
	v_writelane_b32 v244, s52, 20
	v_writelane_b32 v245, s53, 20
	v_cmp_le_u32_e64 s[52:53], s2, v218
	v_writelane_b32 v244, s8, 21
	v_writelane_b32 v245, s9, 21
	v_cmp_le_u32_e64 s[8:9], s2, v217
	v_writelane_b32 v244, s50, 22
	v_writelane_b32 v245, s51, 22
	v_cmp_le_u32_e64 s[50:51], s2, v216
	v_writelane_b32 v244, s52, 23
	v_writelane_b32 v245, s53, 23
	v_cmp_le_u32_e64 s[52:53], s2, v215
	v_writelane_b32 v244, s8, 24
	v_writelane_b32 v245, s9, 24
	v_cmp_le_u32_e64 s[8:9], s2, v214
	v_writelane_b32 v244, s50, 25
	v_writelane_b32 v245, s51, 25
	v_cmp_le_u32_e64 s[50:51], s2, v213
	v_writelane_b32 v244, s52, 26
	v_writelane_b32 v245, s53, 26
	v_cmp_le_u32_e64 s[52:53], s2, v212
	v_writelane_b32 v244, s8, 27
	v_writelane_b32 v245, s9, 27
	v_cmp_le_u32_e64 s[8:9], s2, v77
	v_writelane_b32 v244, s50, 28
	v_writelane_b32 v245, s51, 28
	s_nop 1
	v_writelane_b32 v244, s52, 29
	v_writelane_b32 v245, s53, 29
	s_nop 1
	v_writelane_b32 v244, s8, 30
	v_writelane_b32 v245, s9, 30
	v_lshl_add_u32 v242, v130, 3, s6
	s_mov_b64 s[50:51], exec
	s_mov_b64 exec, 0x7fffffff
	ds_write_b64 v242, v[244:245]
	s_mov_b64 exec, s[50:51]
	v_cmp_le_u32_e64 s[8:9], s2, v76
	s_mov_b64 s[76:77], s[72:73]
	s_branch .LBB0_2093
	v_cmp_le_u32_e64 s[8:9], s2, v241
	s_and_saveexec_b64 s[4:5], s[72:73]
	s_cbranch_execz .LBB0_1783
	v_mov_b32_e32 v242, s6
	v_mov_b64_e32 v[244:245], s[8:9]
	ds_write_b64 v242, v[244:245]
	s_or_b64 exec, exec, s[4:5]
	v_cmp_le_u32_e64 s[8:9], s2, v240
	s_and_saveexec_b64 s[4:5], s[72:73]
	s_cbranch_execnz .LBB0_1784

.LBB0_2097:
	s_or_b64 exec, exec, s[8:9]
	s_cmp_lg_u32 s0, 0
	s_cselect_b64 s[2:3], -1, 0
	s_and_b64 s[2:3], s[2:3], s[70:71]
	s_andn2_b64 vcc, exec, s[2:3]
	s_cbranch_vccz .LBB0_2133
	s_max_u32 s2, s0, 1
	v_cmp_le_u32_e64 s[10:11], s2, v211
	v_cmp_le_u32_e64 s[50:51], s2, v108
	v_cmp_le_u32_e64 s[52:53], s2, v107
	v_writelane_b32 v214, s10, 0
	v_writelane_b32 v215, s11, 0
	v_cmp_le_u32_e64 s[10:11], s2, v106
	v_writelane_b32 v214, s50, 1
	v_writelane_b32 v215, s51, 1
	v_cmp_le_u32_e64 s[50:51], s2, v105
	v_writelane_b32 v214, s52, 2
	v_writelane_b32 v215, s53, 2
	v_cmp_le_u32_e64 s[52:53], s2, v104
	v_writelane_b32 v214, s10, 3
	v_writelane_b32 v215, s11, 3
	v_cmp_le_u32_e64 s[10:11], s2, v103
	v_writelane_b32 v214, s50, 4
	v_writelane_b32 v215, s51, 4
	v_cmp_le_u32_e64 s[50:51], s2, v102
	v_writelane_b32 v214, s52, 5
	v_writelane_b32 v215, s53, 5
	v_cmp_le_u32_e64 s[52:53], s2, v101
	v_writelane_b32 v214, s10, 6
	v_writelane_b32 v215, s11, 6
	v_cmp_le_u32_e64 s[10:11], s2, v100
	v_writelane_b32 v214, s50, 7
	v_writelane_b32 v215, s51, 7
	v_cmp_le_u32_e64 s[50:51], s2, v99
	v_writelane_b32 v214, s52, 8
	v_writelane_b32 v215, s53, 8
	v_cmp_le_u32_e64 s[52:53], s2, v98
	v_writelane_b32 v214, s10, 9
	v_writelane_b32 v215, s11, 9
	v_cmp_le_u32_e64 s[10:11], s2, v97
	v_writelane_b32 v214, s50, 10
	v_writelane_b32 v215, s51, 10
	v_cmp_le_u32_e64 s[50:51], s2, v96
	v_writelane_b32 v214, s52, 11
	v_writelane_b32 v215, s53, 11
	v_cmp_le_u32_e64 s[52:53], s2, v95
	v_writelane_b32 v214, s10, 12
	v_writelane_b32 v215, s11, 12
	v_cmp_le_u32_e64 s[10:11], s2, v94
	v_writelane_b32 v214, s50, 13
	v_writelane_b32 v215, s51, 13
	v_cmp_le_u32_e64 s[50:51], s2, v93
	v_writelane_b32 v214, s52, 14
	v_writelane_b32 v215, s53, 14
	v_cmp_le_u32_e64 s[52:53], s2, v92
	v_writelane_b32 v214, s10, 15
	v_writelane_b32 v215, s11, 15
	v_cmp_le_u32_e64 s[10:11], s2, v91
	v_writelane_b32 v214, s50, 16
	v_writelane_b32 v215, s51, 16
	v_cmp_le_u32_e64 s[50:51], s2, v90
	v_writelane_b32 v214, s52, 17
	v_writelane_b32 v215, s53, 17
	v_cmp_le_u32_e64 s[52:53], s2, v89
	v_writelane_b32 v214, s10, 18
	v_writelane_b32 v215, s11, 18
	v_cmp_le_u32_e64 s[10:11], s2, v88
	v_writelane_b32 v214, s50, 19
	v_writelane_b32 v215, s51, 19
	v_cmp_le_u32_e64 s[50:51], s2, v87
	v_writelane_b32 v214, s52, 20
	v_writelane_b32 v215, s53, 20
	v_cmp_le_u32_e64 s[52:53], s2, v86
	v_writelane_b32 v214, s10, 21
	v_writelane_b32 v215, s11, 21
	v_cmp_le_u32_e64 s[10:11], s2, v85
	v_writelane_b32 v214, s50, 22
	v_writelane_b32 v215, s51, 22
	v_cmp_le_u32_e64 s[50:51], s2, v84
	v_writelane_b32 v214, s52, 23
	v_writelane_b32 v215, s53, 23
	v_cmp_le_u32_e64 s[52:53], s2, v83
	v_writelane_b32 v214, s10, 24
	v_writelane_b32 v215, s11, 24
	v_cmp_le_u32_e64 s[10:11], s2, v82
	v_writelane_b32 v214, s50, 25
	v_writelane_b32 v215, s51, 25
	v_cmp_le_u32_e64 s[50:51], s2, v81
	v_writelane_b32 v214, s52, 26
	v_writelane_b32 v215, s53, 26
	v_cmp_le_u32_e64 s[52:53], s2, v80
	v_writelane_b32 v214, s10, 27
	v_writelane_b32 v215, s11, 27
	v_cmp_le_u32_e64 s[10:11], s2, v79
	v_writelane_b32 v214, s50, 28
	v_writelane_b32 v215, s51, 28
	s_nop 1
	v_writelane_b32 v214, s52, 29
	v_writelane_b32 v215, s53, 29
	s_nop 1
	v_writelane_b32 v214, s10, 30
	v_writelane_b32 v215, s11, 30
	v_lshl_add_u32 v212, v130, 3, s6
	s_mov_b64 s[50:51], exec
	s_mov_b64 exec, 0x7fffffff
	ds_write_b64 v212, v[214:215] offset:256
	s_mov_b64 exec, s[50:51]
	v_cmp_le_u32_e64 s[10:11], s2, v78
	s_mov_b64 s[76:77], s[72:73]
	s_branch .LBB0_2131
	v_cmp_le_u32_e64 s[10:11], s2, v211
	s_and_saveexec_b64 s[8:9], s[72:73]
	s_cbranch_execz .LBB0_2139
	v_mov_b32_e32 v212, s6
	v_mov_b64_e32 v[214:215], s[10:11]
	ds_write_b64 v212, v[214:215] offset:256
	s_or_b64 exec, exec, s[8:9]
	v_cmp_le_u32_e64 s[10:11], s2, v108
	s_and_saveexec_b64 s[8:9], s[72:73]
	s_cbranch_execnz .LBB0_2140
